# move gate|up-0 conversion items [0x5000,0x7600) from P1 to P2's idle half round (128 idle WGs run P1's generic conversion loop; regs saved in v254 lanes)
# speedup vs baseline: 1.0074x; 1.0013x over previous
.LBB0_77:
	s_mov_b32 s101, 0
	s_cmp_gt_i32 s96, 1
	s_cselect_b64 s[0:1], -1, 0
	s_cmp_lt_i32 s97, 2
	s_cselect_b64 s[2:3], -1, 0
	s_or_b64 s[0:1], s[0:1], s[2:3]
	s_and_b64 vcc, exec, s[0:1]
	s_cbranch_vccnz .LBB0_170
	s_cmpk_gt_u32 s63, 0x7f
	s_mov_b64 s[0:1], -1
	s_cbranch_scc0 .LBB0_83
	s_mul_i32 s0, s94, 6
	s_add_i32 s0, s93, s0
	s_add_i32 s30, s0, -2
	s_cmpk_gt_i32 s30, 0x1fff
	s_cbranch_scc1 .LBB0_82
	s_add_u32 s0, s84, 0x48c00000
	s_addc_u32 s1, s85, 0
	s_add_u32 s2, s84, 0x48c20000
	s_addc_u32 s3, s85, 0
	s_add_u32 s4, s84, 0x48d20000
	s_addc_u32 s5, s85, 0
	v_lshrrev_b32_e32 v1, 2, v0
	s_add_u32 s6, s84, 0x48c10000
	v_and_b32_e32 v2, 12, v1
	v_and_b32_e32 v1, 3, v0
	v_lshrrev_b32_e32 v4, 1, v154
	s_mul_i32 s22, s93, 0x2200
	s_addc_u32 s7, s85, 0
	v_and_or_b32 v5, v4, 4, v1
	s_add_i32 s22, s22, 0
	v_lshrrev_b32_e32 v3, 5, v154
	v_or_b32_e32 v87, 0x2000, v5
	v_or_b32_e32 v89, 0x2008, v5
	s_movk_i32 s24, 0x440
	v_mov_b32_e32 v5, s22
	v_mad_u32_u24 v9, v3, s24, v5
	s_add_u32 s24, s90, 0x9170000
	s_addc_u32 s25, s91, 0
	v_and_b32_e32 v68, 31, v0
	v_mov_b32_e32 v71, 0
	v_lshlrev_b32_e32 v70, 2, v2
	v_and_b32_e32 v1, 2, v4
	v_lshrrev_b32_e32 v4, 4, v0
	s_add_u32 s26, s90, 0x9970000
	s_waitcnt lgkmcnt(0)
	v_lshl_add_u64 v[72:73], s[48:49], 0, v[70:71]
	v_lshl_add_u64 v[74:75], s[18:19], 0, v[70:71]
	v_lshlrev_b32_e32 v8, 2, v68
	v_and_or_b32 v69, v4, 1, v1
	v_lshlrev_b32_e32 v91, 1, v3
	s_addc_u32 s27, s91, 0
	v_lshlrev_b32_e32 v4, 3, v3
	v_and_b32_e32 v3, 15, v0
	s_movk_i32 s22, 0x110
	v_lshlrev_b32_e32 v70, 1, v2
	s_add_u32 s28, s84, 0x49100000
	v_mad_u32_u24 v3, v3, s22, v5
	v_and_b32_e32 v5, 48, v0
	v_lshl_add_u64 v[6:7], s[84:85], 0, v[70:71]
	s_mov_b64 s[34:35], 0x33800000
	v_add_u32_e32 v101, v9, v8
	s_movk_i32 s31, 0x2000
	s_mov_b32 s23, 0
	s_addc_u32 s29, s85, 0
	v_lshl_add_u64 v[76:77], v[6:7], 0, s[34:35]
	s_mul_i32 s33, s92, 6
	v_lshlrev_b32_e32 v93, 4, v154
	v_mov_b32_e32 v97, s11
	v_mov_b32_e32 v98, s9
	v_mov_b32_e32 v99, s10
	v_mov_b32_e32 v100, s8
	v_lshlrev_b32_e32 v70, 2, v4
	v_lshlrev_b32_e32 v78, 2, v2
	v_mov_b32_e32 v79, v71
	v_add_u32_e32 v102, v3, v5
	v_add_u32_e32 v103, 0x800, v101
	v_add_u32_e32 v104, 0xa00, v101
	v_add_u32_e32 v105, 0x1000, v101
	v_add_u32_e32 v106, 0x1400, v101
	v_add_u32_e32 v107, 0x1800, v101
	v_add_u32_e32 v108, 0x1a00, v101
	v_add_u32_e32 v109, 0x1c00, v101

.LBB0_89:
	v_lshlrev_b32_e32 v1, 2, v0
	s_cmpk_eq_i32 s92, 0x100
	s_movk_i32 s0, 0x5000
	v_and_b32_e32 v68, 28, v1
	s_cselect_b32 s4, s0, 0xa100
	s_ashr_i32 s30, s94, 31
	s_ashr_i32 s31, s92, 31
	v_and_b32_e32 v66, 56, v0
	v_mov_b32_e32 v71, 0
	v_lshlrev_b32_e32 v70, 2, v68
	s_cmp_lg_u64 s[20:21], 0
	s_waitcnt lgkmcnt(0)
	v_lshl_add_u64 v[72:73], s[50:51], 0, v[70:71]
	v_lshlrev_b32_e32 v70, 1, v66
	s_mov_b32 s5, 0
	s_cselect_b64 s[2:3], -1, 0
	s_add_u32 s33, s84, 0x25400000
	v_lshl_add_u64 v[2:3], s[84:85], 0, v[70:71]
	s_mov_b64 s[6:7], 0x1000000
	v_cmp_eq_u32_e64 s[0:1], 0, v154
	s_addc_u32 s34, s85, 0
	v_lshl_add_u64 v[74:75], v[2:3], 0, s[6:7]
	s_add_i32 s35, 0, 0x20190
	v_mov_b64_e32 v[76:77], s[4:5]
	s_movk_i32 s36, 0x2b00
	s_movk_i32 s37, 0x5000
	s_mov_b32 s38, 0xa000
	s_mov_b32 s39, 0x10000
	s_mov_b32 s40, 0xac000
	s_mov_b32 s41, 0xb1000
	s_mov_b32 s42, 0xb6000
	s_mov_b64 s[4:5], 0xbc200
	s_mov_b32 s43, 0x15800
	s_movk_i32 s44, 0x1000
	s_mov_b64 s[6:7], 0x80
	s_mov_b32 s45, 0x11000
	s_mov_b64 s[12:13], 0x11800
	v_lshlrev_b32_e32 v70, 2, v68
	v_lshlrev_b32_e32 v78, 1, v66
	s_branch .LBB0_92

.LBB0_120:
	s_cmp_eq_u32 s101, 3
	s_cbranch_scc1 .Lp2_conv_ret
	s_cmp_lt_i32 s97, 3
	s_cbranch_scc1 .LBB0_170
	s_waitcnt vmcnt(0)
	v_cmp_eq_u32_e32 vcc, 0, v0
	s_barrier
	s_and_saveexec_b64 s[0:1], vcc
	s_cbranch_execz .LBB0_169
	v_readlane_b32 s2, v240, 12
	s_waitcnt vmcnt(0) expcnt(0) lgkmcnt(0)
	s_nop 0
	v_mov_b32_e32 v1, s2
	ds_read_b32 v3, v1
	ds_read_b32 v1, v1 offset:4
	s_waitcnt lgkmcnt(1)
	v_cmp_ne_u32_e32 vcc, 0, v3
	s_cbranch_vccnz .LBB0_137
	v_readlane_b32 s2, v240, 0
	v_readlane_b32 s3, v240, 1
	s_load_dwordx2 s[6:7], s[2:3], 0x4
	s_add_u32 s2, s84, 0x4200
	s_addc_u32 s3, s85, 0
	s_add_u32 s4, s84, 0x4400
	s_addc_u32 s5, s85, 0
	s_waitcnt lgkmcnt(0)
	s_mul_i32 s33, s6, s92
	s_add_u32 s6, s84, 0x4500
	s_mul_i32 s33, s33, s7
	s_addc_u32 s7, s85, 0
	s_add_u32 s12, s84, 0x4600
	s_addc_u32 s13, s85, 0
	s_add_u32 s14, s84, 0x4700
	s_addc_u32 s15, s85, 0
	s_add_u32 s22, s84, 0x4800
	s_addc_u32 s23, s85, 0
	s_add_u32 s24, s84, 0x4900
	s_addc_u32 s25, s85, 0
	s_add_u32 s26, s84, 0x4a00
	s_addc_u32 s27, s85, 0
	s_add_u32 s28, s84, 0x4b00
	s_addc_u32 s29, s85, 0
	s_add_u32 s30, s84, 0x4c00
	s_addc_u32 s31, s85, 0
	s_add_u32 s34, s84, 0x4d00
	s_addc_u32 s35, s85, 0
	s_add_u32 s36, s84, 0x4e00
	s_addc_u32 s37, s85, 0
	s_add_u32 s38, s84, 0x4f00
	s_addc_u32 s39, s85, 0
	s_add_u32 s40, s84, 0x5000
	s_addc_u32 s41, s85, 0
	s_add_u32 s42, s84, 0x5100
	s_addc_u32 s43, s85, 0
	s_add_u32 s44, s84, 0x5200
	s_addc_u32 s45, s85, 0
	s_add_u32 s46, s84, 0x5300
	s_addc_u32 s47, s85, 0
	s_mov_b32 s56, 1
	v_mov_b32_e32 v17, 0
	s_branch .LBB0_125

.LBB0_251:
	s_cmpk_lg_i32 s92, 0x100
	s_cselect_b64 s[0:1], -1, 0
	s_cmpk_lt_i32 s87, 0x80
	s_cselect_b64 s[2:3], -1, 0
	s_or_b64 s[0:1], s[2:3], s[0:1]
	s_and_b64 vcc, exec, s[0:1]
	s_cbranch_vccnz .LBB0_262
	s_mov_b32 s3, 0
	v_cmp_eq_u32_e32 vcc, 0, v0
	s_waitcnt lgkmcnt(0)
	s_barrier
	s_and_saveexec_b64 s[0:1], vcc
	s_add_i32 s2, 0, 0x20190
	v_mov_b32_e32 v2, 0
	v_mov_b32_e32 v3, s2
	ds_write_b32 v3, v2
	s_or_b64 exec, exec, s[0:1]
	v_and_b32_e32 v1, 28, v1
	v_readlane_b32 s24, v240, 2
	v_and_b32_e32 v10, 56, v0
	v_lshlrev_b32_e32 v2, 2, v1
	v_mov_b32_e32 v3, 0
	v_readlane_b32 s30, v240, 8
	v_readlane_b32 s31, v240, 9
	v_readlane_b32 s25, v240, 3
	s_mov_b64 s[6:7], 0x1a800000
	v_lshl_add_u64 v[4:5], s[30:31], 0, v[2:3]
	v_lshlrev_b32_e32 v2, 1, v10
	v_lshl_add_u64 v[6:7], s[84:85], 0, v[2:3]
	s_add_i32 s12, s87, 0x7580
	v_cmp_eq_u32_e64 s[0:1], 0, v154
	v_lshl_add_u64 v[6:7], v[6:7], 0, s[6:7]
	s_add_i32 s13, 0, 0x20190
	v_mov_b64_e32 v[8:9], 0xa0ff
	s_movk_i32 s14, 0x5000
	s_mov_b32 s15, 0xa000
	s_mov_b32 s22, 0x10000
	s_mov_b32 s23, 0xac000
	s_mov_b32 s24, 0xb1000
	s_mov_b32 s25, 0xb6000
	s_waitcnt lgkmcnt(0)
	s_barrier
	v_readlane_b32 s26, v240, 4
	v_readlane_b32 s27, v240, 5
	v_readlane_b32 s28, v240, 6
	v_readlane_b32 s29, v240, 7
	v_writelane_b32 v254, s4, 0
	v_writelane_b32 v254, s5, 1
	v_writelane_b32 v254, s33, 2
	v_writelane_b32 v254, s34, 3
	v_writelane_b32 v254, s35, 4
	v_writelane_b32 v254, s36, 5
	v_writelane_b32 v254, s37, 6
	v_writelane_b32 v254, s38, 7
	v_writelane_b32 v254, s39, 8
	v_writelane_b32 v254, s40, 9
	v_writelane_b32 v254, s41, 10
	v_writelane_b32 v254, s42, 11
	v_writelane_b32 v254, s43, 12
	v_writelane_b32 v254, s44, 13
	v_writelane_b32 v254, s45, 14
	v_writelane_b32 v254, s46, 15
	v_writelane_b32 v254, s47, 16
	v_writelane_b32 v254, s48, 17
	v_writelane_b32 v254, s49, 18
	v_writelane_b32 v254, s52, 19
	v_writelane_b32 v254, s53, 20
	v_writelane_b32 v254, s54, 21
	v_writelane_b32 v254, s55, 22
	v_writelane_b32 v254, s56, 23
	v_writelane_b32 v254, s57, 24
	v_writelane_b32 v254, s58, 25
	v_writelane_b32 v254, s59, 26
	v_writelane_b32 v254, s92, 27
	v_writelane_b32 v254, s94, 28
	s_movk_i32 s92, 0x80
	s_add_i32 s94, s87, 0x4f80
	s_mov_b32 s101, 3
	s_branch .LBB0_89
.Lp2_conv_ret:
	v_readlane_b32 s4, v254, 0
	v_readlane_b32 s5, v254, 1
	v_readlane_b32 s33, v254, 2
	v_readlane_b32 s34, v254, 3
	v_readlane_b32 s35, v254, 4
	v_readlane_b32 s36, v254, 5
	v_readlane_b32 s37, v254, 6
	v_readlane_b32 s38, v254, 7
	v_readlane_b32 s39, v254, 8
	v_readlane_b32 s40, v254, 9
	v_readlane_b32 s41, v254, 10
	v_readlane_b32 s42, v254, 11
	v_readlane_b32 s43, v254, 12
	v_readlane_b32 s44, v254, 13
	v_readlane_b32 s45, v254, 14
	v_readlane_b32 s46, v254, 15
	v_readlane_b32 s47, v254, 16
	v_readlane_b32 s48, v254, 17
	v_readlane_b32 s49, v254, 18
	v_readlane_b32 s52, v254, 19
	v_readlane_b32 s53, v254, 20
	v_readlane_b32 s54, v254, 21
	v_readlane_b32 s55, v254, 22
	v_readlane_b32 s56, v254, 23
	v_readlane_b32 s57, v254, 24
	v_readlane_b32 s58, v254, 25
	v_readlane_b32 s59, v254, 26
	v_readlane_b32 s92, v254, 27
	v_readlane_b32 s94, v254, 28
	s_mov_b32 s101, 0
	s_branch .LBB0_262
